# v66 + mixer queue order: differential-attention items dequeued before the Fourier GEMM units
# baseline (speedup 1.0000x reference)
.LBB0_94:
	s_barrier
	s_mov_b64 s[0:1], exec
	v_readfirstlane_b32 s98, v155
	s_lshr_b32 s98, s98, 6
	s_cmp_lg_u32 s98, 0
	s_cbranch_scc1 .LBB0_98
	s_waitcnt vmcnt(0)
	v_readlane_b32 s98, v255, 32
	s_cmp_ge_u32 s98, 0x300
	s_cbranch_scc1 .Ldq_nomap
	s_add_i32 s99, s98, 0x100
	s_sub_i32 s98, s98, 0x200
	s_cmp_lt_i32 s98, 0
	s_cselect_b32 s98, s99, s98
.Ldq_nomap:
	v_readlane_b32 s99, v253, 61
	s_mov_b32 s2, 0
	s_mov_b32 s3, 1
	s_mov_b64 exec, s[2:3]
	v_mov_b32_e32 v0, s98
	v_mov_b32_e32 v2, s99
	ds_write_b32 v2, v0
	global_atomic_add v255, v1, v157, s[64:65] sc0

.Ldl_ctxaddr:
	s_sub_i32 s20, s3, 63
	s_lshl_b64 s[4:5], s[20:21], 15
	v_lshl_add_u64 v[66:67], v[172:173], 0, s[4:5]
	s_branch .LBB0_232
	s_nop 0
	s_nop 0
	s_nop 0
	s_nop 0
	s_nop 0
	s_nop 0
	s_nop 0
	s_nop 0
	s_nop 0
	s_nop 0
	s_nop 0
	s_nop 0
	s_nop 0
	s_nop 0
	s_nop 0
	s_nop 0
	s_nop 0
	s_nop 0
	s_nop 0
	s_nop 0
	s_nop 0
	s_nop 0
	s_nop 0
.LBB0_229:
	v_mov_b64_e32 v[174:175], v[182:183]
	s_cmpk_lg_i32 s3, 0x43
	s_cselect_b64 s[0:1], -1, 0
	s_cmpk_eq_i32 s3, 0x43
	s_cbranch_scc1 .LBB0_233
